# mLSTM state images (FIMG) re-laid out lane-linear so pass1 stores / pass2 loads are 1 KB-contiguous per instruction
# speedup vs baseline: 1.0215x; 1.0008x over previous
; __device__ __forceinline__ void mlstm_pass1(const bf16_t* PR, const bf16_t* QC, const bf16_t* KC, const float* Gt, const float* gain, bf16_t* Y, LAS unsigned char* lds, ...
;     ...
;         if (w < 5) {
; #pragma unroll
;             for (int i = 0; i < 4; ++i)
; #pragma unroll
;                 for (int e = 0; e < 16; e += 4) *(f32x4*)(FIMG + ((size_t)(st * 5 + w) * 64 + lane) * 64 + i * 16 + e) = (f32x4){C[i][e], C[i][e + 1], C[i][e + 2], C[i][e + 3]};
;         }
.LBB0_491:
	s_and_b64 vcc, exec, s[76:77]
	s_cbranch_vccnz .LBB0_493
	s_mul_i32 s0, s90, 5
	s_add_i32 s0, s0, s93
	s_ashr_i32 s1, s0, 31
	s_lshl_b64 s[0:1], s[0:1], 14
	v_lshl_add_u64 v[64:65], v[148:149], 0, s[0:1]
	v_mbcnt_lo_u32_b32 v204, -1, 0
	v_mbcnt_hi_u32_b32 v204, -1, v204
	v_mul_u32_u24_e32 v204, 0xf0, v204
	v_sub_co_u32_e32 v64, vcc, v64, v204
	s_nop 1
	v_subbrev_co_u32_e32 v65, vcc, 0, v65, vcc
	s_mov_b64 s[0:1], 0x1000
	global_store_dwordx4 v[64:65], v[32:35], off
	global_store_dwordx4 v[64:65], v[36:39], off offset:1024
	global_store_dwordx4 v[64:65], v[40:43], off offset:2048
	global_store_dwordx4 v[64:65], v[44:47], off offset:3072
	v_lshl_add_u64 v[64:65], v[64:65], 0, s[0:1]
	global_store_dwordx4 v[64:65], v[48:51], off
	global_store_dwordx4 v[64:65], v[52:55], off offset:1024
	global_store_dwordx4 v[64:65], v[56:59], off offset:2048
	global_store_dwordx4 v[64:65], v[60:63], off offset:3072
	v_lshl_add_u64 v[64:65], v[64:65], 0, s[0:1]
	global_store_dwordx4 v[64:65], v[16:19], off
	global_store_dwordx4 v[64:65], v[20:23], off offset:1024
	global_store_dwordx4 v[64:65], v[24:27], off offset:2048
	global_store_dwordx4 v[64:65], v[28:31], off offset:3072
	v_lshl_add_u64 v[64:65], v[64:65], 0, s[0:1]
	global_store_dwordx4 v[64:65], v[0:3], off
	global_store_dwordx4 v[64:65], v[4:7], off offset:1024
	global_store_dwordx4 v[64:65], v[8:11], off offset:2048
	global_store_dwordx4 v[64:65], v[12:15], off offset:3072

; __device__ __forceinline__ void mlstm_pass2(const bf16_t* PR, const bf16_t* QC, const float* gain, bf16_t* Y, LAS unsigned char* lds,
;                                             float* NB, const float* DEN, const float* BC, const float* FIMG, const float* DSEG, int st_first, int st_stride) {
;     ...
;             for (int j = 0; j < seg; ++j) { const int stj = (st & ~3) + j; const float dj = __expf(DSEG[stj]);
; #pragma unroll
;                 for (int i = 0; i < 4; ++i)
; #pragma unroll
;                     for (int e = 0; e < 16; e += 4) { const f32x4 fv = *(const f32x4*)(FIMG + ((size_t)(stj * 5 + w) * 64 + lane) * 64 + i * 16 + e);
; #pragma unroll
;                         for (int k = 0; k < 4; ++k) S[i][e + k] = dj * S[i][e + k] + fv[k]; } }
.LBB0_567:
	v_mov_b64_e32 v[64:65], s[2:3]
	global_load_dword v184, v[64:65], off
	s_ashr_i32 s1, s0, 31
	s_lshl_b64 s[40:41], s[0:1], 14
	v_lshl_add_u64 v[206:207], v[108:109], 0, s[40:41]
	v_mbcnt_lo_u32_b32 v204, -1, 0
	v_mbcnt_hi_u32_b32 v204, -1, v204
	v_mul_u32_u24_e32 v204, 0xf0, v204
	v_sub_co_u32_e32 v206, vcc, v206, v204
	s_nop 1
	v_subbrev_co_u32_e32 v207, vcc, 0, v207, vcc
	s_mov_b64 s[40:41], 0x1000
	global_load_dwordx4 v[64:67], v[206:207], off
	global_load_dwordx4 v[68:71], v[206:207], off offset:1024
	global_load_dwordx4 v[72:75], v[206:207], off offset:2048
	global_load_dwordx4 v[76:79], v[206:207], off offset:3072
	v_lshl_add_u64 v[206:207], v[206:207], 0, s[40:41]
	global_load_dwordx4 v[92:95], v[206:207], off
	global_load_dwordx4 v[88:91], v[206:207], off offset:1024
	global_load_dwordx4 v[84:87], v[206:207], off offset:2048
	global_load_dwordx4 v[80:83], v[206:207], off offset:3072
	v_lshl_add_u64 v[206:207], v[206:207], 0, s[40:41]
	global_load_dwordx4 v[164:167], v[206:207], off
	global_load_dwordx4 v[160:163], v[206:207], off offset:1024
	global_load_dwordx4 v[100:103], v[206:207], off offset:2048
	global_load_dwordx4 v[96:99], v[206:207], off offset:3072
	v_lshl_add_u64 v[206:207], v[206:207], 0, s[40:41]
	global_load_dwordx4 v[180:183], v[206:207], off
	global_load_dwordx4 v[176:179], v[206:207], off offset:1024
	global_load_dwordx4 v[172:175], v[206:207], off offset:2048
	global_load_dwordx4 v[168:171], v[206:207], off offset:3072
	s_add_i32 s9, s9, -1
	s_add_i32 s0, s0, 5
	s_add_u32 s2, s2, 4
	s_addc_u32 s3, s3, 0
	s_cmp_eq_u32 s9, 0
	s_waitcnt vmcnt(0) lgkmcnt(0)
	v_mul_f32_e32 v184, 0x3fb8aa3b, v184
	v_exp_f32_e32 v184, v184
	s_nop 0
	v_pk_fma_f32 v[16:17], v[16:17], v[184:185], v[64:65] op_sel_hi:[1,0,1]
	v_pk_fma_f32 v[62:63], v[62:63], v[184:185], v[66:67] op_sel_hi:[1,0,1]
	v_pk_fma_f32 v[18:19], v[18:19], v[184:185], v[68:69] op_sel_hi:[1,0,1]
	v_pk_fma_f32 v[60:61], v[60:61], v[184:185], v[70:71] op_sel_hi:[1,0,1]
	v_pk_fma_f32 v[20:21], v[20:21], v[184:185], v[72:73] op_sel_hi:[1,0,1]
	v_pk_fma_f32 v[58:59], v[58:59], v[184:185], v[74:75] op_sel_hi:[1,0,1]
	v_pk_fma_f32 v[22:23], v[22:23], v[184:185], v[76:77] op_sel_hi:[1,0,1]
	v_pk_fma_f32 v[24:25], v[24:25], v[184:185], v[78:79] op_sel_hi:[1,0,1]
	v_pk_fma_f32 v[30:31], v[30:31], v[184:185], v[80:81] op_sel_hi:[1,0,1]
	v_pk_fma_f32 v[28:29], v[28:29], v[184:185], v[84:85] op_sel_hi:[1,0,1]
	v_pk_fma_f32 v[26:27], v[26:27], v[184:185], v[88:89] op_sel_hi:[1,0,1]
	v_pk_fma_f32 v[56:57], v[56:57], v[184:185], v[92:93] op_sel_hi:[1,0,1]
	v_pk_fma_f32 v[48:49], v[48:49], v[184:185], v[82:83] op_sel_hi:[1,0,1]
	v_pk_fma_f32 v[50:51], v[50:51], v[184:185], v[86:87] op_sel_hi:[1,0,1]
	v_pk_fma_f32 v[52:53], v[52:53], v[184:185], v[90:91] op_sel_hi:[1,0,1]
	v_pk_fma_f32 v[54:55], v[54:55], v[184:185], v[94:95] op_sel_hi:[1,0,1]
	v_pk_fma_f32 v[38:39], v[38:39], v[184:185], v[96:97] op_sel_hi:[1,0,1]
	v_pk_fma_f32 v[36:37], v[36:37], v[184:185], v[100:101] op_sel_hi:[1,0,1]
	v_pk_fma_f32 v[34:35], v[34:35], v[184:185], v[160:161] op_sel_hi:[1,0,1]
	v_pk_fma_f32 v[32:33], v[32:33], v[184:185], v[164:165] op_sel_hi:[1,0,1]
	v_pk_fma_f32 v[40:41], v[40:41], v[184:185], v[98:99] op_sel_hi:[1,0,1]
	v_pk_fma_f32 v[42:43], v[42:43], v[184:185], v[102:103] op_sel_hi:[1,0,1]
	v_pk_fma_f32 v[44:45], v[44:45], v[184:185], v[162:163] op_sel_hi:[1,0,1]
	v_pk_fma_f32 v[46:47], v[46:47], v[184:185], v[166:167] op_sel_hi:[1,0,1]
	v_pk_fma_f32 v[2:3], v[2:3], v[184:185], v[168:169] op_sel_hi:[1,0,1]
	v_pk_fma_f32 v[6:7], v[6:7], v[184:185], v[172:173] op_sel_hi:[1,0,1]
	v_pk_fma_f32 v[10:11], v[10:11], v[184:185], v[176:177] op_sel_hi:[1,0,1]
	v_pk_fma_f32 v[14:15], v[14:15], v[184:185], v[180:181] op_sel_hi:[1,0,1]
	v_pk_fma_f32 v[0:1], v[0:1], v[184:185], v[170:171] op_sel_hi:[1,0,1]
	v_pk_fma_f32 v[4:5], v[4:5], v[184:185], v[174:175] op_sel_hi:[1,0,1]
	v_pk_fma_f32 v[8:9], v[8:9], v[184:185], v[178:179] op_sel_hi:[1,0,1]
	v_pk_fma_f32 v[12:13], v[12:13], v[184:185], v[182:183] op_sel_hi:[1,0,1]
	s_cbranch_scc0 .LBB0_567
	s_branch .LBB0_569
